# second-half K fragment addresses precomputed at the loop edge so their LDS reads issue first at the section start
# baseline (speedup 1.0000x reference)
; #define LAS __attribute__((address_space(3)))
; #define WAIT_BAR() asm volatile("s_waitcnt vmcnt(0) lgkmcnt(0)\n\ts_barrier" ::: "memory")
; #define BMODE(t) do { if constexpr (DIFF) { const int dd = (t) * 64 - qw; float cbn; if (dd <= -191) { bm = 1; cbn = bL; } else if (dd >= 159) { bm = 1; cbn = bR; } else { bm = 2; cbn = 0.f; } \
;             ix = dd - r32 + 256 + 4 * hi; if (cbn != cb) { cb = cbn; moved = true; } } } while (0)
; #define NEGM() do { if (moved) { const float v_ = cb - m_reg; _Pragma("unroll") for (int r = 0; r < 16; ++r) negm[r] = v_; asm volatile("" : "+v"(negm)); } } while (0)
; #define WAIT_BAR() asm volatile("s_waitcnt vmcnt(0) lgkmcnt(0)\n\ts_barrier" ::: "memory")
; #define MFMA32(a, b, c) __builtin_amdgcn_mfma_f32_32x32x16_bf16(a, b, c, 0, 0, 0)
; #define BMODE(t) do { if constexpr (DIFF) { const int dd = (t) * 64 - qw; float cbn; if (dd <= -191) { bm = 1; cbn = bL; } else if (dd >= 159) { bm = 1; cbn = bR; } else { bm = 2; cbn = 0.f; } \
;             ix = dd - r32 + 256 + 4 * hi; if (cbn != cb) { cb = cbn; moved = true; } } } while (0)
; template <int NCB, bool DIFF, bool STAT>
; __device__ __forceinline__ void attn_unit(LAS char* lds, const Params& P, int s, int head, int qb, float sref) {
;     ...
;         f32x16 negm;
; #pragma unroll
;         for (int d = 0; d < NCB; ++d) o[d] = f32x16{};
;         f32x16 pA0, pA1, pB0, pB1; float alA = 1.f, alB = 1.f;
;         u32x4 pw[4];
;         int bm = 0, ix = 0;
;         WAIT_BAR();
;         BMODE(0); NEGM();
;         { const LAS char* kp_ = kp0;
; #pragma unroll
;           for (int d0 = 0; d0 < 4; ++d0) { const bf16x8 b0 = *(const LAS bf16x8*)(kp_ + d0 * 2048), b1 = *(const LAS bf16x8*)(kp_ + d0 * 2048 + 512);
;               if (d0 == 0) { if constexpr (ZREF) { pA0 = MFMA32(b0, qr[0], f32x16{}); pA1 = MFMA32(b1, qr[0], f32x16{}); } else { pA0 = MFMA32(b0, qr[0], negm); pA1 = MFMA32(b1, qr[0], negm); } } else { pA0 = MFMA32(b0, qr[d0], pA0); pA1 = MFMA32(b1, qr[d0], pA1); } } }
;         bias_add<DIFF>(pA0, pA1, bm, tab, ix);
;         if constexpr (!STAT) rowmax_decide<DIFF, true>(pA0, pA1, m_reg, alA, moved, bm, tab, ix); else moved = false;
; #pragma unroll
;         for (int r = 0; r < 16; ++r) { pA0[r] = __builtin_amdgcn_exp2f(pA0[r]); pA1[r] = __builtin_amdgcn_exp2f(pA1[r]); }
;         int sl_prev = 0, sl_cur = 1;
;         bf16x8 kf[3];
.LBB0_511:
	s_nop 10
	v_exp_f32_e32 v82, v18
	v_exp_f32_e32 v83, v19
	v_exp_f32_e32 v84, v20
	v_exp_f32_e32 v85, v21
	v_exp_f32_e32 v86, v22
	v_exp_f32_e32 v87, v23
	v_exp_f32_e32 v88, v24
	v_exp_f32_e32 v89, v25
	v_exp_f32_e32 v90, v26
	v_exp_f32_e32 v91, v27
	v_exp_f32_e32 v92, v28
	v_exp_f32_e32 v93, v29
	v_exp_f32_e32 v94, v30
	v_exp_f32_e32 v95, v31
	v_exp_f32_e32 v96, v32
	v_exp_f32_e32 v97, v33
	v_exp_f32_e32 v98, v2
	v_exp_f32_e32 v99, v3
	v_exp_f32_e32 v100, v4
	v_exp_f32_e32 v101, v5
	v_exp_f32_e32 v102, v6
	v_exp_f32_e32 v103, v7
	v_exp_f32_e32 v104, v8
	v_exp_f32_e32 v105, v9
	v_exp_f32_e32 v106, v10
	v_exp_f32_e32 v107, v11
	v_exp_f32_e32 v108, v12
	v_exp_f32_e32 v109, v13
	v_exp_f32_e32 v110, v14
	v_exp_f32_e32 v111, v15
	v_exp_f32_e32 v112, v16
	v_exp_f32_e32 v113, v17
	s_xor_b64 s[42:43], s[46:47], -1
	s_add_u32 s46, s40, 0x8000
	v_mov_b32_e32 v216, 0
	v_mov_b32_e32 v240, 0
	v_mov_b32_e32 v241, 0
	v_mov_b32_e32 v242, 0
	v_mov_b32_e32 v243, 0
	v_and_b32_e32 v236, 15, v230
	v_bfe_u32 v237, v230, 4, 1
	v_mov_b32_e32 v238, 0x3f803f80
	v_cmp_eq_u32_e64 s[98:99], v236, v237
	s_nop 1
	v_cndmask_b32_e64 v236, 0, v238, s[98:99]
	v_mov_b32_e32 v237, v236
	v_mov_b32_e32 v238, v236
	v_mov_b32_e32 v239, v236
	s_addc_u32 s47, s41, 0
	s_mov_b32 s14, 1
	s_mov_b32 s9, 0
	s_mov_b32 s67, 4
	s_mov_b64 s[40:41], s[48:49]
	s_mov_b32 s66, s8
	v_mov_b32_e32 v218, v215
	v_mov_b32_e32 v166, v209
	v_mov_b32_e32 v50, 0
	v_mov_b32_e32 v51, v216
	v_mov_b32_e32 v52, v216
	v_mov_b32_e32 v53, v216
	v_mov_b32_e32 v54, v216
	v_mov_b32_e32 v55, v216
	v_mov_b32_e32 v56, v216
	v_mov_b32_e32 v57, v216
	v_mov_b32_e32 v58, v216
	v_mov_b32_e32 v59, v216
	v_mov_b32_e32 v60, v216
	v_mov_b32_e32 v61, v216
	v_mov_b32_e32 v62, v216
	v_mov_b32_e32 v63, v216
	v_mov_b32_e32 v64, v216
	v_mov_b32_e32 v65, v216
	v_mov_b32_e32 v66, 0
	v_mov_b32_e32 v67, v216
	v_mov_b32_e32 v68, v216
	v_mov_b32_e32 v69, v216
	v_mov_b32_e32 v70, v216
	v_mov_b32_e32 v71, v216
	v_mov_b32_e32 v72, v216
	v_mov_b32_e32 v73, v216
	v_mov_b32_e32 v74, v216
	v_mov_b32_e32 v75, v216
	v_mov_b32_e32 v76, v216
	v_mov_b32_e32 v77, v216
	v_mov_b32_e32 v78, v216
	v_mov_b32_e32 v79, v216
	v_mov_b32_e32 v80, v216
	v_mov_b32_e32 v81, v216
	v_mov_b32_e32 v2, 0
	v_mov_b32_e32 v3, v216
	v_mov_b32_e32 v4, v216
	v_mov_b32_e32 v5, v216
	v_mov_b32_e32 v6, v216
	v_mov_b32_e32 v7, v216
	v_mov_b32_e32 v8, v216
	v_mov_b32_e32 v9, v216
	v_mov_b32_e32 v10, v216
	v_mov_b32_e32 v11, v216
	v_mov_b32_e32 v12, v216
	v_mov_b32_e32 v13, v216
	v_mov_b32_e32 v14, v216
	v_mov_b32_e32 v15, v216
	v_mov_b32_e32 v16, v216
	v_mov_b32_e32 v17, v216
	v_mov_b32_e32 v18, 0
	v_mov_b32_e32 v19, v216
	v_mov_b32_e32 v20, v216
	v_mov_b32_e32 v21, v216
	v_mov_b32_e32 v22, v216
	v_mov_b32_e32 v23, v216
	v_mov_b32_e32 v24, v216
	v_mov_b32_e32 v25, v216
	v_mov_b32_e32 v26, v216
	v_mov_b32_e32 v27, v216
	v_mov_b32_e32 v28, v216
	v_mov_b32_e32 v29, v216
	v_mov_b32_e32 v30, v216
	v_mov_b32_e32 v31, v216
	v_mov_b32_e32 v32, v216
	v_mov_b32_e32 v33, v216
	s_add_i32 s4, s14, 1
	s_cmp_lg_u32 s14, 4
	s_cselect_b32 s4, s4, 0
	v_lshl_add_u32 v219, s4, 13, v205
	s_branch .LBB0_513
.LBB0_512:
	s_waitcnt lgkmcnt(2)
	v_mfma_f32_32x32x16_bf16 v[50:65], v[162:165], v[122:125], v[50:65]
	ds_read_b64_tr_b16 v[126:127], v222 offset:1024
	ds_read_b64_tr_b16 v[128:129], v222 offset:3072
	v_mfma_f32_16x16x32_bf16 v[240:243], v[114:117], v[236:239], v[240:243]
	v_cndmask_b32_e64 v166, v221, v223, s[4:5]
	v_exp_f32_e32 v98, v98
	v_exp_f32_e32 v99, v99
	s_waitcnt lgkmcnt(2)
	v_mfma_f32_32x32x16_bf16 v[66:81], v[162:165], v[118:121], v[66:81]
	ds_read_b64_tr_b16 v[122:123], v222 offset:1536
	ds_read_b64_tr_b16 v[124:125], v222 offset:3584
	v_exp_f32_e32 v100, v100
	v_exp_f32_e32 v101, v101
	s_waitcnt lgkmcnt(2)
	v_mfma_f32_32x32x16_bf16 v[2:17], v[162:165], v[126:129], v[2:17]
	ds_read_b64_tr_b16 v[118:119], v222 offset:4096
	ds_read_b64_tr_b16 v[120:121], v222 offset:6144
	v_exp_f32_e32 v102, v102
	v_exp_f32_e32 v103, v103
	s_waitcnt lgkmcnt(2)
	v_mfma_f32_32x32x16_bf16 v[18:33], v[162:165], v[122:125], v[18:33]
	ds_read_b64_tr_b16 v[126:127], v222 offset:4608
	ds_read_b64_tr_b16 v[128:129], v222 offset:6656
	v_exp_f32_e32 v104, v104
	v_exp_f32_e32 v105, v105
	s_waitcnt lgkmcnt(2)
	v_mfma_f32_32x32x16_bf16 v[50:65], v[134:137], v[118:121], v[50:65]
	ds_read_b64_tr_b16 v[122:123], v222 offset:5120
	ds_read_b64_tr_b16 v[124:125], v222 offset:7168
	v_exp_f32_e32 v106, v106
	v_exp_f32_e32 v107, v107
	s_waitcnt lgkmcnt(2)
	v_mfma_f32_32x32x16_bf16 v[66:81], v[134:137], v[126:129], v[66:81]
	ds_read_b64_tr_b16 v[118:119], v222 offset:5632
	ds_read_b64_tr_b16 v[120:121], v222 offset:7680
	v_exp_f32_e32 v108, v108
	v_exp_f32_e32 v109, v109
	s_waitcnt lgkmcnt(2)
	v_mfma_f32_32x32x16_bf16 v[2:17], v[134:137], v[122:125], v[2:17]
	ds_read_b64_tr_b16 v[126:127], v222 offset:8192
	ds_read_b64_tr_b16 v[128:129], v222 offset:10240
	v_exp_f32_e32 v110, v110
	v_exp_f32_e32 v111, v111
	s_waitcnt lgkmcnt(2)
	v_mfma_f32_32x32x16_bf16 v[18:33], v[134:137], v[118:121], v[18:33]
	ds_read_b64_tr_b16 v[122:123], v222 offset:8704
	ds_read_b64_tr_b16 v[124:125], v222 offset:10752
	v_exp_f32_e32 v112, v112
	v_exp_f32_e32 v113, v113
	s_waitcnt lgkmcnt(2)
	v_mfma_f32_32x32x16_bf16 v[50:65], v[130:133], v[126:129], v[50:65]
	ds_read_b64_tr_b16 v[118:119], v222 offset:9216
	ds_read_b64_tr_b16 v[120:121], v222 offset:11264
	v_exp_f32_e32 v82, v82
	v_exp_f32_e32 v83, v83
	s_waitcnt lgkmcnt(2)
	v_mfma_f32_32x32x16_bf16 v[66:81], v[130:133], v[122:125], v[66:81]
	ds_read_b64_tr_b16 v[126:127], v222 offset:9728
	ds_read_b64_tr_b16 v[128:129], v222 offset:11776
	v_exp_f32_e32 v84, v84
	v_exp_f32_e32 v85, v85
	s_waitcnt lgkmcnt(2)
	v_mfma_f32_32x32x16_bf16 v[2:17], v[130:133], v[118:121], v[2:17]
	ds_read_b64_tr_b16 v[122:123], v222 offset:12288
	ds_read_b64_tr_b16 v[124:125], v222 offset:14336
	v_exp_f32_e32 v86, v86
	v_exp_f32_e32 v87, v87
	s_waitcnt lgkmcnt(2)
	v_mfma_f32_32x32x16_bf16 v[18:33], v[130:133], v[126:129], v[18:33]
	ds_read_b64_tr_b16 v[118:119], v222 offset:12800
	ds_read_b64_tr_b16 v[120:121], v222 offset:14848
	v_exp_f32_e32 v88, v88
	v_exp_f32_e32 v89, v89
	s_waitcnt lgkmcnt(2)
	v_mfma_f32_32x32x16_bf16 v[50:65], v[114:117], v[122:125], v[50:65]
	ds_read_b64_tr_b16 v[126:127], v222 offset:13312
	ds_read_b64_tr_b16 v[128:129], v222 offset:15360
	v_exp_f32_e32 v90, v90
	v_exp_f32_e32 v91, v91
	s_waitcnt lgkmcnt(2)
	v_mfma_f32_32x32x16_bf16 v[66:81], v[114:117], v[118:121], v[66:81]
	ds_read_b64_tr_b16 v[122:123], v222 offset:13824
	ds_read_b64_tr_b16 v[124:125], v222 offset:15872
	v_exp_f32_e32 v92, v92
	v_exp_f32_e32 v93, v93
	s_waitcnt lgkmcnt(2)
	v_mfma_f32_32x32x16_bf16 v[2:17], v[114:117], v[126:129], v[2:17]
	v_exp_f32_e32 v94, v94
	v_exp_f32_e32 v95, v95
	s_waitcnt lgkmcnt(0)
	v_mfma_f32_32x32x16_bf16 v[18:33], v[114:117], v[122:125], v[18:33]
	v_exp_f32_e32 v96, v96
	v_exp_f32_e32 v97, v97
	s_add_i32 s4, s9, 1
	s_cmp_lg_u32 s9, 4
	s_cselect_b32 s14, s4, 0
	s_add_i32 s67, s67, 2
	s_addk_i32 s66, 0x80
	s_add_u32 s40, s40, 0x8000
	s_addc_u32 s41, s41, 0
	s_add_u32 s46, s46, 0x4000
	s_addc_u32 s47, s47, 0
	v_add_u32_e32 v218, 0x200, v218
	s_add_i32 s4, s14, 1
	s_cmp_lg_u32 s14, 4
	s_cselect_b32 s4, s4, 0
	v_lshl_add_u32 v219, s4, 13, v205
	s_and_b64 vcc, exec, s[50:51]
	s_waitcnt vmcnt(0) lgkmcnt(0)
	s_barrier
	s_cbranch_vccnz .LBB0_525

.LBB0_519:
	s_waitcnt lgkmcnt(2)
	v_mfma_f32_32x32x16_bf16 v[50:65], v[162:165], v[86:89], v[50:65]
	ds_read_b64_tr_b16 v[94:95], v167 offset:1024
	ds_read_b64_tr_b16 v[96:97], v167 offset:3072
	v_mfma_f32_16x16x32_bf16 v[240:243], v[82:85], v[236:239], v[240:243]
	v_exp_f32_e32 v130, v130
	v_exp_f32_e32 v131, v131
	v_cndmask_b32_e64 v221, v166, v168, s[4:5]
	s_waitcnt lgkmcnt(2)
	v_mfma_f32_32x32x16_bf16 v[66:81], v[162:165], v[90:93], v[66:81]
	ds_read_b64_tr_b16 v[86:87], v167 offset:1536
	ds_read_b64_tr_b16 v[88:89], v167 offset:3584
	v_exp_f32_e32 v132, v132
	v_exp_f32_e32 v133, v133
	s_waitcnt lgkmcnt(2)
	v_mfma_f32_32x32x16_bf16 v[2:17], v[162:165], v[94:97], v[2:17]
	ds_read_b64_tr_b16 v[90:91], v167 offset:4096
	ds_read_b64_tr_b16 v[92:93], v167 offset:6144
	v_exp_f32_e32 v134, v134
	v_exp_f32_e32 v135, v135
	s_waitcnt lgkmcnt(2)
	v_mfma_f32_32x32x16_bf16 v[18:33], v[162:165], v[86:89], v[18:33]
	ds_read_b64_tr_b16 v[94:95], v167 offset:4608
	ds_read_b64_tr_b16 v[96:97], v167 offset:6656
	v_exp_f32_e32 v136, v136
	v_exp_f32_e32 v137, v137
	s_waitcnt lgkmcnt(2)
	v_mfma_f32_32x32x16_bf16 v[50:65], v[102:105], v[90:93], v[50:65]
	ds_read_b64_tr_b16 v[86:87], v167 offset:5120
	ds_read_b64_tr_b16 v[88:89], v167 offset:7168
	v_exp_f32_e32 v138, v138
	v_exp_f32_e32 v139, v139
	s_waitcnt lgkmcnt(2)
	v_mfma_f32_32x32x16_bf16 v[66:81], v[102:105], v[94:97], v[66:81]
	ds_read_b64_tr_b16 v[90:91], v167 offset:5632
	ds_read_b64_tr_b16 v[92:93], v167 offset:7680
	v_exp_f32_e32 v140, v140
	v_exp_f32_e32 v141, v141
	s_waitcnt lgkmcnt(2)
	v_mfma_f32_32x32x16_bf16 v[2:17], v[102:105], v[86:89], v[2:17]
	ds_read_b64_tr_b16 v[94:95], v167 offset:8192
	ds_read_b64_tr_b16 v[96:97], v167 offset:10240
	v_exp_f32_e32 v142, v142
	v_exp_f32_e32 v143, v143
	s_waitcnt lgkmcnt(2)
	v_mfma_f32_32x32x16_bf16 v[18:33], v[102:105], v[90:93], v[18:33]
	ds_read_b64_tr_b16 v[86:87], v167 offset:8704
	ds_read_b64_tr_b16 v[88:89], v167 offset:10752
	v_exp_f32_e32 v144, v144
	v_exp_f32_e32 v145, v145
	s_waitcnt lgkmcnt(2)
	v_mfma_f32_32x32x16_bf16 v[50:65], v[98:101], v[94:97], v[50:65]
	ds_read_b64_tr_b16 v[90:91], v167 offset:9216
	ds_read_b64_tr_b16 v[92:93], v167 offset:11264
	v_exp_f32_e32 v114, v114
	v_exp_f32_e32 v115, v115
	s_waitcnt lgkmcnt(2)
	v_mfma_f32_32x32x16_bf16 v[66:81], v[98:101], v[86:89], v[66:81]
	ds_read_b64_tr_b16 v[94:95], v167 offset:9728
	ds_read_b64_tr_b16 v[96:97], v167 offset:11776
	v_exp_f32_e32 v116, v116
	v_exp_f32_e32 v117, v117
	s_waitcnt lgkmcnt(2)
	v_mfma_f32_32x32x16_bf16 v[2:17], v[98:101], v[90:93], v[2:17]
	ds_read_b64_tr_b16 v[86:87], v167 offset:12288
	ds_read_b64_tr_b16 v[88:89], v167 offset:14336
	v_exp_f32_e32 v118, v118
	v_exp_f32_e32 v119, v119
	s_waitcnt lgkmcnt(2)
	v_mfma_f32_32x32x16_bf16 v[18:33], v[98:101], v[94:97], v[18:33]
	ds_read_b64_tr_b16 v[90:91], v167 offset:12800
	ds_read_b64_tr_b16 v[92:93], v167 offset:14848
	v_exp_f32_e32 v120, v120
	v_exp_f32_e32 v121, v121
	s_waitcnt lgkmcnt(2)
	v_mfma_f32_32x32x16_bf16 v[50:65], v[82:85], v[86:89], v[50:65]
	ds_read_b64_tr_b16 v[94:95], v167 offset:13312
	ds_read_b64_tr_b16 v[96:97], v167 offset:15360
	v_exp_f32_e32 v122, v122
	v_exp_f32_e32 v123, v123
	s_waitcnt lgkmcnt(2)
	v_mfma_f32_32x32x16_bf16 v[66:81], v[82:85], v[90:93], v[66:81]
	ds_read_b64_tr_b16 v[86:87], v167 offset:13824
	ds_read_b64_tr_b16 v[88:89], v167 offset:15872
	v_exp_f32_e32 v124, v124
	v_exp_f32_e32 v125, v125
	s_waitcnt lgkmcnt(2)
	v_mfma_f32_32x32x16_bf16 v[2:17], v[82:85], v[94:97], v[2:17]
	v_exp_f32_e32 v126, v126
	v_exp_f32_e32 v127, v127
	s_waitcnt lgkmcnt(0)
	v_mfma_f32_32x32x16_bf16 v[18:33], v[82:85], v[86:89], v[18:33]
	v_exp_f32_e32 v128, v128
	v_exp_f32_e32 v129, v129
	ds_read_b128 v[82:85], v219
	ds_read_b128 v[166:169], v219 offset:512
	s_add_i32 s9, s14, 1
	s_add_i32 s4, s66, 0xffffff42
	s_cmpk_lt_i32 s4, 0xff42
	s_cselect_b64 vcc, -1, 0
	s_cmpk_gt_i32 s4, 0x9e
	s_cselect_b64 s[4:5], -1, 0
	v_cndmask_b32_e64 v86, 0, v207, s[4:5]
	v_cndmask_b32_e32 v223, v86, v206, vcc
	v_cmp_eq_f32_e32 vcc, v223, v221
	v_cmp_neq_f32_e64 s[4:5], v223, v221
	s_cbranch_vccnz .LBB0_521
	v_sub_f32_e32 v34, v223, v217
	v_mov_b32_e32 v35, v34
	v_mov_b32_e32 v36, v34
	v_mov_b32_e32 v37, v34
	v_mov_b32_e32 v38, v34
	v_mov_b32_e32 v39, v34
	v_mov_b32_e32 v40, v34
	v_mov_b32_e32 v41, v34
	v_mov_b32_e32 v42, v34
	v_mov_b32_e32 v43, v34
	v_mov_b32_e32 v44, v34
	v_mov_b32_e32 v45, v34
	v_mov_b32_e32 v46, v34
	v_mov_b32_e32 v47, v34
	v_mov_b32_e32 v48, v34
	v_mov_b32_e32 v49, v34

; #define LAS __attribute__((address_space(3)))
; #define WAIT_BAR() asm volatile("s_waitcnt vmcnt(0) lgkmcnt(0)\n\ts_barrier" ::: "memory")
; #define WAIT_BAR() asm volatile("s_waitcnt vmcnt(0) lgkmcnt(0)\n\ts_barrier" ::: "memory")
; template <int NCB, bool DIFF, bool STAT>
; __device__ __forceinline__ void attn_unit(LAS char* lds, const Params& P, int s, int head, int qb, float sref) {
;     ...
;         const unsigned dvoff = (unsigned)(wid * 1024 + lane * 16);
;         const unsigned kdst = lds0 + L_K + wid * 1024, vdst = lds0 + L_V + wid * 1024;
;     ...
;         __syncthreads();
;         DMA(0, 0); DMA(1, 1); DMA(2, 2);
;         bf16x8 qr[4];
; #pragma unroll
;         for (int d0 = 0; d0 < 4; ++d0) qr[d0] = *(const bf16x8*)(Qw + (size_t)r32 * 64 + d0 * 16 + hi * 8);
;         constexpr bool ZREF = STAT && !DIFF;
;         float m_reg = (STAT && !ZREF) ? sref : 0.f, l_reg = 0.f, cb = 0.f; bool moved = true;
;         if constexpr (STAT && DIFF) {
;             float q2 = 0.f;
; #pragma unroll
;             for (int d0 = 0; d0 < 4; ++d0)
; #pragma unroll
;                 for (int i = 0; i < 8; ++i) { const float f = __builtin_bit_cast(float, (unsigned)(unsigned short)qr[d0][i] << 16); q2 += f * f; }
;             { auto rr = __builtin_amdgcn_permlane32_swap(__float_as_uint(q2), __float_as_uint(q2), false, false); q2 = __uint_as_float(rr[0]) + __uint_as_float(rr[1]); }
;             const float kn2 = __uint_as_float(((const unsigned*)(ws + WS_BAR))[3800 + s * 8 + head * 2 + mp]);
;             m_reg = __builtin_sqrtf(q2 * kn2) * 1.001f + 0.01f + sref;
;         }
;         f32x16 negm;
; #pragma unroll
;         for (int d = 0; d < NCB; ++d) o[d] = f32x16{};
;         f32x16 pA0, pA1, pB0, pB1; float alA = 1.f, alB = 1.f;
;         u32x4 pw[4];
;         int bm = 0, ix = 0;
;         WAIT_BAR();
;         BMODE(0); NEGM();
;         { const LAS char* kp_ = kp0;
; #pragma unroll
;           for (int d0 = 0; d0 < 4; ++d0) { const bf16x8 b0 = *(const LAS bf16x8*)(kp_ + d0 * 2048), b1 = *(const LAS bf16x8*)(kp_ + d0 * 2048 + 512);
;               if (d0 == 0) { if constexpr (ZREF) { pA0 = MFMA32(b0, qr[0], f32x16{}); pA1 = MFMA32(b1, qr[0], f32x16{}); } else { pA0 = MFMA32(b0, qr[0], negm); pA1 = MFMA32(b1, qr[0], negm); } } else { pA0 = MFMA32(b0, qr[d0], pA0); pA1 = MFMA32(b1, qr[d0], pA1); } } }
.LBB0_588:
	v_readlane_b32 s4, v254, 45
	v_readlane_b32 s5, v254, 46
	s_lshl_b32 s8, s64, 14
	s_nop 3
	global_load_dword v1, v0, s[4:5]
	s_lshl_b32 s4, s64, 12
	s_add_i32 s9, s4, 0x6000
	s_cmp_lt_u32 s64, 2
	s_cselect_b64 s[4:5], -1, 0
	s_and_b64 s[6:7], s[4:5], exec
	s_mov_b32 s6, 0x42200000
	s_cselect_b32 s48, 0x100, 64
	s_cselect_b32 s14, s8, s9
	s_lshl_b32 s42, s63, 8
	s_waitcnt vmcnt(0)
	v_cmp_nge_f32_e32 vcc, s6, v1
	s_cbranch_vccnz .LBB0_595
	v_mov_b32_e32 v42, v230
	s_lshl_b64 s[6:7], s[14:15], 3
	v_readfirstlane_b32 s9, v42
	s_ashr_i32 s8, s9, 6
	s_lshl_b32 s43, s8, 5
	s_add_i32 s43, s43, s42
	s_and_b64 s[12:13], s[4:5], exec
	s_mov_b32 s73, s15
	s_cselect_b32 s40, 14, 12
	s_lshl_b64 s[12:13], s[72:73], s40
	s_add_u32 s6, s6, s12
	s_addc_u32 s7, s7, s13
	s_ashr_i32 s12, s43, 31
	s_add_u32 s6, s6, s43
	s_addc_u32 s7, s7, s12
	s_lshl_b64 s[6:7], s[6:7], 7
	s_add_u32 s12, s92, s6
	s_addc_u32 s13, s93, s7
	s_lshr_b32 s6, s72, 2
	s_mov_b32 s7, s15
	s_lshl_b64 s[6:7], s[6:7], s40
	s_lshl_b64 s[40:41], s[14:15], 8
	s_lshl_b64 s[6:7], s[6:7], 7
	s_add_u32 s6, s40, s6
	s_addc_u32 s7, s41, s7
	v_readlane_b32 s16, v254, 47
	s_add_u32 s40, s16, s6
	v_readlane_b32 s16, v254, 48
	s_addc_u32 s41, s16, s7
	v_readlane_b32 s16, v254, 49
	v_and_b32_e32 v133, 63, v42
	s_add_u32 s6, s16, s6
	v_readlane_b32 s16, v254, 50
	v_lshlrev_b32_e32 v43, 4, v133
	s_addc_u32 s7, s16, s7
	s_lshl_b32 s47, s8, 10
	v_or_b32_e32 v134, s47, v43
	s_add_i32 s46, s47, s65
	s_add_i32 s47, s47, 0
	s_add_u32 s50, s40, 0x2000
	s_addc_u32 s51, s41, 0
	s_add_u32 s54, s6, 0x2000
	s_addc_u32 s55, s7, 0
	s_add_u32 s56, s40, 0x4000
	v_and_b32_e32 v132, 31, v42
	s_addc_u32 s57, s41, 0
	s_barrier
	s_mov_b32 s8, m0
	s_mov_b32 m0, s46
	s_nop 0
	global_load_lds_dwordx4 v134, s[40:41]
	s_mov_b32 m0, s8
	s_add_u32 s58, s6, 0x4000
	v_lshlrev_b32_e32 v2, 7, v132
	v_mov_b32_e32 v3, v0
	s_mov_b32 s8, m0
	s_mov_b32 m0, s47
	s_nop 0
	global_load_lds_dwordx4 v134, s[6:7]
	s_mov_b32 m0, s8
	s_addc_u32 s59, s7, 0
	v_lshl_add_u64 v[2:3], s[12:13], 0, v[2:3]
	s_add_i32 s8, s47, 0x16000
	s_mov_b32 s12, m0
	s_mov_b32 m0, s8
	s_nop 0
	global_load_lds_dwordx4 v134, s[50:51]
	s_mov_b32 m0, s12
	v_bfe_u32 v150, v42, 5, 1
	s_add_i32 s8, s47, 0x4000
	s_mov_b32 s12, m0
	s_mov_b32 m0, s8
	s_nop 0
	global_load_lds_dwordx4 v134, s[54:55]
	s_mov_b32 m0, s12
	v_lshlrev_b32_e32 v148, 4, v150
	v_mov_b32_e32 v149, v0
	s_add_i32 s8, s47, 0x18000
	s_mov_b32 s12, m0
	s_mov_b32 m0, s8
	s_nop 0
	global_load_lds_dwordx4 v134, s[56:57]
	s_mov_b32 m0, s12
	v_lshl_add_u64 v[6:7], v[2:3], 0, v[148:149]
	s_add_i32 s8, s47, 0x8000
	s_mov_b32 s12, m0
	s_mov_b32 m0, s8
	s_nop 0
	global_load_lds_dwordx4 v134, s[58:59]
	s_mov_b32 m0, s12
	global_load_dwordx4 v[124:127], v[6:7], off
	global_load_dwordx4 v[120:123], v[6:7], off offset:32
	global_load_dwordx4 v[116:119], v[6:7], off offset:64
	global_load_dwordx4 v[112:115], v[6:7], off offset:96
	v_mov_b32_e32 v2, v0
	v_mov_b32_e32 v3, v0
	v_mov_b32_e32 v4, v0
	v_mov_b32_e32 v5, v0
	v_mov_b32_e32 v6, v0
	v_mov_b32_e32 v7, v0
	v_mov_b32_e32 v8, v0
	v_mov_b32_e32 v9, v0
	v_mov_b32_e32 v10, v0
	v_mov_b32_e32 v11, v0
	v_mov_b32_e32 v12, v0
	v_mov_b32_e32 v13, v0
	v_mov_b32_e32 v14, v0
	v_mov_b32_e32 v15, v0
	v_mov_b32_e32 v1, v0
	v_mov_b64_e32 v[16:17], v[14:15]
	v_mov_b64_e32 v[14:15], v[12:13]
	v_mov_b64_e32 v[12:13], v[10:11]
	v_mov_b64_e32 v[10:11], v[8:9]
	v_mov_b64_e32 v[8:9], v[6:7]
	v_mov_b64_e32 v[6:7], v[4:5]
	v_mov_b64_e32 v[4:5], v[2:3]
	v_mov_b64_e32 v[2:3], v[0:1]
	v_lshlrev_b32_e32 v1, 10, v150
	v_lshlrev_b32_e32 v18, 4, v132
	v_add3_u32 v135, s65, v1, v18
	s_waitcnt vmcnt(0) lgkmcnt(0)
	s_barrier
	ds_read_b128 v[2:5], v135
	ds_read_b128 v[18:21], v135 offset:512
	ds_read_b128 v[34:37], v135 offset:2048
	ds_read_b128 v[38:41], v135 offset:2560
	s_add_i32 s50, s48, -1
	v_lshlrev_b32_e32 v1, 1, v42
	v_lshlrev_b32_e32 v42, 3, v133
	s_add_u32 s6, s6, 0x8000
	s_addc_u32 s7, s7, 0
	v_and_b32_e32 v1, 32, v1
	s_add_u32 s40, s40, 0x8000
	s_mov_b32 s49, 4
	s_mov_b32 s8, 1
	s_mov_b32 s54, 0
	s_addc_u32 s41, s41, 0
	s_waitcnt vmcnt(3) lgkmcnt(3)
	v_mfma_f32_32x32x16_bf16 v[2:17], v[2:5], v[124:127], 0
	s_waitcnt lgkmcnt(2)
	v_mfma_f32_32x32x16_bf16 v[18:33], v[18:21], v[124:127], 0
	s_waitcnt vmcnt(2) lgkmcnt(1)
	v_mfma_f32_32x32x16_bf16 v[2:17], v[34:37], v[120:123], v[2:17]
	s_waitcnt lgkmcnt(0)
	v_mfma_f32_32x32x16_bf16 v[18:33], v[38:41], v[120:123], v[18:33]
	ds_read_b128 v[34:37], v135 offset:4096
	ds_read_b128 v[38:41], v135 offset:4608
	s_waitcnt vmcnt(1) lgkmcnt(1)
	v_mfma_f32_32x32x16_bf16 v[2:17], v[34:37], v[116:119], v[2:17]
	ds_read_b128 v[34:37], v135 offset:6144
	s_waitcnt lgkmcnt(1)
	v_mfma_f32_32x32x16_bf16 v[18:33], v[38:41], v[116:119], v[18:33]
	ds_read_b128 v[38:41], v135 offset:6656
	s_waitcnt vmcnt(0) lgkmcnt(1)
	v_mfma_f32_32x32x16_bf16 v[2:17], v[34:37], v[112:115], v[2:17]
	v_and_b32_e32 v34, 24, v42
	v_and_b32_e32 v35, 0xc0, v43
	v_and_b32_e32 v36, 0x100, v42
	v_add3_u32 v34, 0, v34, v35
	v_add3_u32 v1, v34, v1, v36
	s_nop 6
	v_exp_f32_e32 v64, v2
	s_waitcnt lgkmcnt(0)
; template <int NCB, bool DIFF, bool STAT>
; __device__ __forceinline__ void attn_unit(LAS char* lds, const Params& P, int s, int head, int qb, float sref) {
;     ...
;         if constexpr (!STAT) rowmax_decide<DIFF, true>(pA0, pA1, m_reg, alA, moved, bm, tab, ix); else moved = false;
; #pragma unroll
;         for (int r = 0; r < 16; ++r) { pA0[r] = __builtin_amdgcn_exp2f(pA0[r]); pA1[r] = __builtin_amdgcn_exp2f(pA1[r]); }
;         int sl_prev = 0, sl_cur = 1;
;         bf16x8 kf[3];
	v_mfma_f32_32x32x16_bf16 v[18:33], v[38:41], v[112:115], v[18:33]
	v_exp_f32_e32 v65, v3
	v_exp_f32_e32 v66, v4
	v_exp_f32_e32 v67, v5
	v_exp_f32_e32 v68, v6
	v_exp_f32_e32 v69, v7
	v_exp_f32_e32 v70, v8
	v_exp_f32_e32 v71, v9
	s_nop 4
	v_exp_f32_e32 v48, v18
	v_exp_f32_e32 v49, v19
	v_exp_f32_e32 v50, v20
	v_exp_f32_e32 v51, v21
	v_exp_f32_e32 v52, v22
	v_exp_f32_e32 v53, v23
	v_exp_f32_e32 v54, v24
	v_exp_f32_e32 v55, v25
	v_exp_f32_e32 v56, v26
	v_exp_f32_e32 v57, v27
	v_exp_f32_e32 v58, v28
	v_exp_f32_e32 v59, v29
	v_exp_f32_e32 v60, v30
	v_exp_f32_e32 v61, v31
	v_exp_f32_e32 v62, v32
	v_exp_f32_e32 v63, v33
	v_exp_f32_e32 v72, v10
	v_exp_f32_e32 v73, v11
	v_exp_f32_e32 v74, v12
	v_exp_f32_e32 v75, v13
	v_exp_f32_e32 v76, v14
	v_exp_f32_e32 v77, v15
	v_exp_f32_e32 v78, v16
	v_exp_f32_e32 v79, v17
	v_mov_b32_e32 v14, 0
	v_mov_b32_e32 v144, 0
	v_mov_b32_e32 v145, 0
	v_mov_b32_e32 v146, 0
	v_mov_b32_e32 v147, 0
	v_and_b32_e32 v140, 15, v230
	v_bfe_u32 v141, v230, 4, 1
	v_mov_b32_e32 v142, 0x3f803f80
	v_cmp_eq_u32_e64 s[98:99], v140, v141
	s_nop 1
	v_cndmask_b32_e64 v140, 0, v142, s[98:99]
	v_mov_b32_e32 v141, v140
	v_mov_b32_e32 v142, v140
	v_mov_b32_e32 v143, v140
	v_mov_b32_e32 v16, 0
	v_mov_b32_e32 v17, v14
	v_mov_b32_e32 v18, v14
	v_mov_b32_e32 v19, v14
	v_mov_b32_e32 v20, v14
	v_mov_b32_e32 v21, v14
	v_mov_b32_e32 v22, v14
	v_mov_b32_e32 v23, v14
	v_mov_b32_e32 v24, v14
	v_mov_b32_e32 v25, v14
	v_mov_b32_e32 v26, v14
	v_mov_b32_e32 v27, v14
	v_mov_b32_e32 v28, v14
	v_mov_b32_e32 v29, v14
	v_mov_b32_e32 v30, v14
	v_mov_b32_e32 v31, v14
	v_mov_b32_e32 v32, 0
	v_mov_b32_e32 v33, v14
	v_mov_b32_e32 v34, v14
	v_mov_b32_e32 v35, v14
	v_mov_b32_e32 v36, v14
	v_mov_b32_e32 v37, v14
	v_mov_b32_e32 v38, v14
	v_mov_b32_e32 v39, v14
	v_mov_b32_e32 v40, v14
	v_mov_b32_e32 v41, v14
	v_mov_b32_e32 v42, v14
	v_mov_b32_e32 v43, v14
	v_mov_b32_e32 v44, v14
	v_mov_b32_e32 v45, v14
	v_mov_b32_e32 v46, v14
	v_mov_b32_e32 v47, v14
	s_lshl_b32 s12, s54, 14
	v_lshl_add_u32 v136, s8, 13, v135
	v_add_u32_e32 v15, s12, v1
	s_add_i32 s13, s8, 1
	s_cmp_lg_u32 s8, 4
	s_cselect_b32 s13, s13, 0
	v_lshl_add_u32 v137, s13, 13, v135
	s_branch .LBB0_591
.LBB0_590:
	s_waitcnt lgkmcnt(2)
	v_mfma_f32_32x32x16_bf16 v[16:31], v[128:131], v[48:51], v[16:31]
	ds_read_b64_tr_b16 v[56:57], v15 offset:2048
	ds_read_b64_tr_b16 v[58:59], v15 offset:3072
	v_mfma_f32_16x16x32_bf16 v[144:147], v[2:5], v[140:143], v[144:147]
	v_exp_f32_e32 v96, v96
	v_exp_f32_e32 v97, v97
	v_exp_f32_e32 v98, v98
	v_exp_f32_e32 v99, v99
	s_waitcnt lgkmcnt(2)
	v_mfma_f32_32x32x16_bf16 v[32:47], v[128:131], v[52:55], v[32:47]
	ds_read_b64_tr_b16 v[48:49], v15 offset:2560
	ds_read_b64_tr_b16 v[50:51], v15 offset:3584
	v_exp_f32_e32 v100, v100
	v_exp_f32_e32 v101, v101
	v_exp_f32_e32 v102, v102
	v_exp_f32_e32 v103, v103
	s_waitcnt lgkmcnt(2)
	v_mfma_f32_32x32x16_bf16 v[16:31], v[10:13], v[56:59], v[16:31]
	ds_read_b64_tr_b16 v[52:53], v15 offset:4096
	ds_read_b64_tr_b16 v[54:55], v15 offset:5120
	v_exp_f32_e32 v104, v104
	v_exp_f32_e32 v105, v105
	v_exp_f32_e32 v106, v106
	v_exp_f32_e32 v107, v107
	s_waitcnt lgkmcnt(2)
	v_mfma_f32_32x32x16_bf16 v[32:47], v[10:13], v[48:51], v[32:47]
	ds_read_b64_tr_b16 v[56:57], v15 offset:4608
	ds_read_b64_tr_b16 v[58:59], v15 offset:5632
	v_exp_f32_e32 v108, v108
	v_exp_f32_e32 v109, v109
	v_exp_f32_e32 v110, v110
	v_exp_f32_e32 v111, v111
	s_waitcnt lgkmcnt(2)
	v_mfma_f32_32x32x16_bf16 v[16:31], v[6:9], v[52:55], v[16:31]
	ds_read_b64_tr_b16 v[10:11], v15 offset:6144
	ds_read_b64_tr_b16 v[12:13], v15 offset:7168
	v_exp_f32_e32 v80, v80
	v_exp_f32_e32 v81, v81
	v_exp_f32_e32 v82, v82
	v_exp_f32_e32 v83, v83
	s_waitcnt lgkmcnt(2)
	v_mfma_f32_32x32x16_bf16 v[32:47], v[6:9], v[56:59], v[32:47]
	ds_read_b64_tr_b16 v[48:49], v15 offset:6656
	ds_read_b64_tr_b16 v[50:51], v15 offset:7680
	v_exp_f32_e32 v84, v84
	v_exp_f32_e32 v85, v85
	v_exp_f32_e32 v86, v86
	v_exp_f32_e32 v87, v87
	s_waitcnt lgkmcnt(2)
	v_mfma_f32_32x32x16_bf16 v[16:31], v[2:5], v[10:13], v[16:31]
	v_exp_f32_e32 v88, v88
	v_exp_f32_e32 v89, v89
	v_exp_f32_e32 v90, v90
	v_exp_f32_e32 v91, v91
	s_waitcnt lgkmcnt(0)
	v_mfma_f32_32x32x16_bf16 v[32:47], v[2:5], v[48:51], v[32:47]
	v_exp_f32_e32 v92, v92
	v_exp_f32_e32 v93, v93
	v_exp_f32_e32 v94, v94
	v_exp_f32_e32 v95, v95
	ds_read_b128 v[2:5], v137
	ds_read_b128 v[6:9], v137 offset:512
	s_add_i32 s13, s8, 1
	s_cmp_lg_u32 s8, 4
	s_cselect_b32 s54, s13, 0
	v_lshl_add_u32 v15, s54, 13, v135
	v_lshl_add_u32 v128, s8, 14, v1
	s_waitcnt lgkmcnt(1)
	v_mfma_f32_32x32x16_bf16 v[64:79], v[2:5], v[124:127], 0
	ds_read_b128 v[10:13], v15 offset:2048
	v_cvt_pk_bf16_f32 v2, v96, v97
	v_cvt_pk_bf16_f32 v3, v98, v99
	s_nop 0
	ds_read_b128 v[96:99], v15 offset:2560
	v_cvt_pk_bf16_f32 v4, v100, v101
	s_waitcnt lgkmcnt(2)
	v_mfma_f32_32x32x16_bf16 v[48:63], v[6:9], v[124:127], 0
	v_cvt_pk_bf16_f32 v5, v102, v103
	s_waitcnt lgkmcnt(1)
	v_mfma_f32_32x32x16_bf16 v[64:79], v[10:13], v[120:123], v[64:79]
	ds_read_b128 v[6:9], v15 offset:4096
	v_mfma_f32_16x16x32_bf16 v[144:147], v[2:5], v[140:143], v[144:147]
	v_cvt_pk_bf16_f32 v10, v104, v105
	v_cvt_pk_bf16_f32 v11, v106, v107
	s_waitcnt lgkmcnt(1)
	v_mfma_f32_32x32x16_bf16 v[48:63], v[96:99], v[120:123], v[48:63]
	ds_read_b128 v[100:103], v15 offset:4608
	v_cvt_pk_bf16_f32 v12, v108, v109
	v_cvt_pk_bf16_f32 v13, v110, v111
	s_waitcnt lgkmcnt(1)
	v_mfma_f32_32x32x16_bf16 v[64:79], v[6:9], v[116:119], v[64:79]
	ds_read_b128 v[96:99], v15 offset:6144
	v_mfma_f32_16x16x32_bf16 v[144:147], v[10:13], v[140:143], v[144:147]
	v_cvt_pk_bf16_f32 v6, v80, v81
	v_cvt_pk_bf16_f32 v7, v82, v83
	s_waitcnt lgkmcnt(1)
	v_mfma_f32_32x32x16_bf16 v[48:63], v[100:103], v[116:119], v[48:63]
	ds_read_b128 v[80:83], v15 offset:6656
	v_cvt_pk_bf16_f32 v8, v84, v85
	v_cvt_pk_bf16_f32 v9, v86, v87
	s_waitcnt lgkmcnt(1)
	v_mfma_f32_32x32x16_bf16 v[64:79], v[96:99], v[112:115], v[64:79]
	v_cvt_pk_bf16_f32 v84, v88, v89
	v_cvt_pk_bf16_f32 v85, v90, v91
	v_mfma_f32_16x16x32_bf16 v[144:147], v[6:9], v[140:143], v[144:147]
	ds_read_b64_tr_b16 v[88:89], v128
	ds_read_b64_tr_b16 v[90:91], v128 offset:1024
	s_waitcnt lgkmcnt(2)
	v_mfma_f32_32x32x16_bf16 v[48:63], v[80:83], v[112:115], v[48:63]
	v_cvt_pk_bf16_f32 v86, v92, v93
	v_cvt_pk_bf16_f32 v87, v94, v95
	ds_read_b64_tr_b16 v[80:81], v128 offset:512
	ds_read_b64_tr_b16 v[82:83], v128 offset:1536
	s_waitcnt lgkmcnt(2)
	v_mfma_f32_32x32x16_bf16 v[16:31], v[2:5], v[88:91], v[16:31]
	ds_read_b64_tr_b16 v[92:93], v128 offset:2048
	ds_read_b64_tr_b16 v[94:95], v128 offset:3072
	v_mfma_f32_16x16x32_bf16 v[144:147], v[84:87], v[140:143], v[144:147]
	v_exp_f32_e32 v64, v64
	v_exp_f32_e32 v65, v65
	v_exp_f32_e32 v66, v66
	v_exp_f32_e32 v67, v67
	s_waitcnt lgkmcnt(2)
	v_mfma_f32_32x32x16_bf16 v[32:47], v[2:5], v[80:83], v[32:47]
	ds_read_b64_tr_b16 v[88:89], v128 offset:2560
	ds_read_b64_tr_b16 v[90:91], v128 offset:3584
	v_exp_f32_e32 v68, v68
	v_exp_f32_e32 v69, v69
	v_exp_f32_e32 v70, v70
	v_exp_f32_e32 v71, v71
	s_waitcnt lgkmcnt(2)
	v_mfma_f32_32x32x16_bf16 v[16:31], v[10:13], v[92:95], v[16:31]
	ds_read_b64_tr_b16 v[2:3], v128 offset:4096
	ds_read_b64_tr_b16 v[4:5], v128 offset:5120
	v_exp_f32_e32 v72, v72
	v_exp_f32_e32 v73, v73
	v_exp_f32_e32 v74, v74
	v_exp_f32_e32 v75, v75
	s_waitcnt lgkmcnt(2)
	v_mfma_f32_32x32x16_bf16 v[32:47], v[10:13], v[88:91], v[32:47]
	ds_read_b64_tr_b16 v[80:81], v128 offset:4608
	ds_read_b64_tr_b16 v[82:83], v128 offset:5632
	v_exp_f32_e32 v76, v76
	v_exp_f32_e32 v77, v77
	v_exp_f32_e32 v78, v78
	v_exp_f32_e32 v79, v79
	s_waitcnt lgkmcnt(2)
	v_mfma_f32_32x32x16_bf16 v[16:31], v[6:9], v[2:5], v[16:31]
	ds_read_b64_tr_b16 v[10:11], v128 offset:6144
	ds_read_b64_tr_b16 v[12:13], v128 offset:7168
	v_exp_f32_e32 v48, v48
	v_exp_f32_e32 v49, v49
	v_exp_f32_e32 v50, v50
	v_exp_f32_e32 v51, v51
	s_waitcnt lgkmcnt(2)
	v_mfma_f32_32x32x16_bf16 v[32:47], v[6:9], v[80:83], v[32:47]
	ds_read_b64_tr_b16 v[2:3], v128 offset:6656
	ds_read_b64_tr_b16 v[4:5], v128 offset:7680
	v_exp_f32_e32 v52, v52
	v_exp_f32_e32 v53, v53
	v_exp_f32_e32 v54, v54
	v_exp_f32_e32 v55, v55
	s_waitcnt lgkmcnt(2)
	v_mfma_f32_32x32x16_bf16 v[16:31], v[84:87], v[10:13], v[16:31]
	v_exp_f32_e32 v56, v56
	v_exp_f32_e32 v57, v57
	v_exp_f32_e32 v58, v58
	v_exp_f32_e32 v59, v59
	s_waitcnt lgkmcnt(0)
	v_mfma_f32_32x32x16_bf16 v[32:47], v[84:87], v[2:5], v[32:47]
	v_exp_f32_e32 v60, v60
	v_exp_f32_e32 v61, v61
	v_exp_f32_e32 v62, v62
	v_exp_f32_e32 v63, v63
	s_add_i32 s8, s54, 1
	s_cmp_lg_u32 s54, 4
	s_cselect_b32 s8, s8, 0
	s_add_u32 s6, s6, 0x4000
	s_addc_u32 s7, s7, 0
	s_add_u32 s40, s40, 0x4000
	s_addc_u32 s41, s41, 0
	s_add_i32 s49, s49, 2
	s_lshl_b32 s12, s54, 14
	v_lshl_add_u32 v136, s8, 13, v135
	v_add_u32_e32 v15, s12, v1
	s_add_i32 s13, s8, 1
	s_cmp_lg_u32 s8, 4
	s_cselect_b32 s13, s13, 0
	v_lshl_add_u32 v137, s13, 13, v135
	s_cmp_lt_u32 s51, s50
	s_waitcnt vmcnt(0) lgkmcnt(0)
	s_barrier
	s_cbranch_scc0 .LBB0_596
